# proj phase: static s_setprio 1 for waves 4-7 (reset at phase end)
# baseline (speedup 1.0000x reference)
.Lpp_norm:
	v_readlane_b32 s4, v249, 49
	s_cmp_eq_u32 s4, 6
	s_cbranch_scc0 .Lprio_pj
	v_readfirstlane_b32 s0, v135
	s_nop 1
	s_lshr_b32 s0, s0, 6
	s_cmp_ge_u32 s0, 4
	s_cbranch_scc0 .Lprio_pj
	s_setprio 1
.Lprio_pj:
	s_cmp_lt_i32 s4, 5
	s_mov_b64 s[4:5], 0
	s_mov_b64 s[38:39], -1
	s_mov_b64 s[0:1], 0
	v_writelane_b32 v249, s4, 56
	s_nop 1
	v_writelane_b32 v249, s5, 57
	s_cbranch_scc1 .LBB0_400
	v_readlane_b32 s4, v249, 49
	s_cmp_gt_i32 s4, 7
	s_mov_b64 s[4:5], 0
	s_mov_b64 s[20:21], 0
	v_writelane_b32 v249, s4, 56
	s_nop 1
	v_writelane_b32 v249, s5, 57
	s_cbranch_scc0 .LBB0_367
	v_readlane_b32 s4, v249, 49
	s_cmp_gt_i32 s4, 8
	s_cbranch_scc0 .LBB0_361
	s_mov_b64 s[24:25], -1
	s_mov_b64 s[36:37], 0
	s_cmp_gt_i32 s4, 9
	s_mov_b64 s[4:5], 0
	s_cbranch_scc0 .LBB0_358
	v_readlane_b32 s4, v249, 49
	s_mov_b64 s[38:39], 0
	s_cmp_eq_u32 s4, 10
	s_mov_b64 s[4:5], 0
	s_cbranch_scc0 .LBB0_358
	s_mov_b64 s[4:5], -1
